# adds: phase P8 (in-place 512-wide MLA rmsnorm) and its grid barrier removed - attention epilogue applies mla_out_g and writes per-row per-head sums of squares (f32), the w_out GEMM scales its f32 accu
# speedup vs baseline: 1.0108x; 1.0108x over previous
; DI float bflo(unsigned u) { return __uint_as_float(u << 16); }
; DI float bfhi(unsigned u) { return __uint_as_float(u & 0xffff0000u); }
; template <int NR> DI void mla_norm_rows(bf16* A, const float* g_mla, int m0, int mstride, int lane) {
;     ...
;     const f32x4 gm0 = *(const f32x4*)(g_mla + 8 * lane), gm1 = *(const f32x4*)(g_mla + 8 * lane + 4);
;     const float gm[8] = {gm0[0], gm0[1], gm0[2], gm0[3], gm1[0], gm1[1], gm1[2], gm1[3]};
; #pragma unroll
;     for (int r = 0; r < NR; ++r) {
;         const u32x4 a = am[r];
;         float v[8] = {bflo(a.x), bfhi(a.x), bflo(a.y), bfhi(a.y), bflo(a.z), bfhi(a.z), bflo(a.w), bfhi(a.w)};
;         float s2 = 0.f;
; #pragma unroll
;         for (int i = 0; i < 8; ++i) s2 += v[i] * v[i];
;         const float rr = rsqrtf(wave_sum(s2) * (1.f / 512.f) + EPS);
;         u32x4 w; w.x = pk2(v[0] * rr * gm[0], v[1] * rr * gm[1]); w.y = pk2(v[2] * rr * gm[2], v[3] * rr * gm[3]); w.z = pk2(v[4] * rr * gm[4], v[5] * rr * gm[5]); w.w = pk2(v[6] * rr * gm[6], v[7] * rr * gm[7]);
; DI void attn_unit(int b, int h, int qb, const bf16* Qb, const bf16* Kb, const bf16* Vt, const int* positions, bf16* O, LAS unsigned char* lds, int tid) {
;     ...
;     lrun += __shfl_xor(lrun, 32);
;     const float inv = 1.0f / lrun;
;     bf16* op = O + (size_t)(rowbase + qrow) * 1024 + h * 64;
; #pragma unroll
;     for (int blk = 0; blk < 2; ++blk)
; #pragma unroll
;         for (int gp = 0; gp < 2; ++gp) {
;             unsigned e0, e1, o0w, o1w;
;             if (blk == 0) { e0 = pk2(o0[8 * gp] * inv, o0[8 * gp + 1] * inv); e1 = pk2(o0[8 * gp + 2] * inv, o0[8 * gp + 3] * inv); o0w = pk2(o0[8 * gp + 4] * inv, o0[8 * gp + 5] * inv); o1w = pk2(o0[8 * gp + 6] * inv, o0[8 * gp + 7] * inv); }
;             else { e0 = pk2(o1[8 * gp] * inv, o1[8 * gp + 1] * inv); e1 = pk2(o1[8 * gp + 2] * inv, o1[8 * gp + 3] * inv); o0w = pk2(o1[8 * gp + 4] * inv, o1[8 * gp + 5] * inv); o1w = pk2(o1[8 * gp + 6] * inv, o1[8 * gp + 7] * inv); }
;             const unsigned send0 = hi ? e0 : o0w, send1 = hi ? e1 : o1w;
;             const unsigned recv0 = (unsigned)__shfl_xor((int)send0, 32), recv1 = (unsigned)__shfl_xor((int)send1, 32);
;             u32x4 w;
;             if (hi == 0) { w.x = e0; w.y = e1; w.z = recv0; w.w = recv1; }
;             else { w.x = recv0; w.y = recv1; w.z = o0w; w.w = o1w; }
;             *(u32x4*)(op + 32 * blk + 16 * gp + 8 * hi) = w;
;         }
.LBB0_869:
	v_and_b32_e32 v2, 64, v213
	v_xor_b32_e32 v0, 32, v213
	v_add_u32_e32 v2, 64, v2
	v_cmp_lt_i32_e32 vcc, v0, v2
	s_lshl_b32 s12, s18, 1
	v_lshl_add_u64 v[2:3], v[180:181], 0, s[12:13]
	v_cndmask_b32_e32 v0, v213, v0, vcc
	v_lshlrev_b32_e32 v14, 2, v0
	ds_bpermute_b32 v0, v14, v48
	s_waitcnt lgkmcnt(0)
	s_barrier
	v_add_f32_e32 v0, v48, v0
	v_div_scale_f32 v4, s[18:19], v0, v0, 1.0
	v_rcp_f32_e32 v5, v4
	s_nop 0
	v_fma_f32 v6, -v4, v5, 1.0
	v_fmac_f32_e32 v5, v6, v5
	v_div_scale_f32 v6, vcc, 1.0, v0, 1.0
	v_mul_f32_e32 v7, v6, v5
	v_fma_f32 v8, -v4, v7, v6
	v_fmac_f32_e32 v7, v8, v5
	v_fma_f32 v4, -v4, v7, v6
	v_div_fmas_f32 v4, v4, v5, v7
	v_div_fixup_f32 v0, v4, v0, 1.0
	s_waitcnt vmcnt(0)
	v_and_b32_e32 v95, 32, v213
	v_lshrrev_b32_e32 v95, 1, v95
	s_lshl_b32 s98, s12, 1
	v_add_u32_e32 v95, s98, v95
	global_load_dwordx4 v[100:103], v95, s[86:87]
	global_load_dwordx4 v[104:107], v95, s[86:87] offset:32
	global_load_dwordx4 v[108:111], v95, s[86:87] offset:64
	global_load_dwordx4 v[112:115], v95, s[86:87] offset:96
	global_load_dwordx4 v[116:119], v95, s[86:87] offset:128
	global_load_dwordx4 v[120:123], v95, s[86:87] offset:160
	global_load_dwordx4 v[124:127], v95, s[86:87] offset:192
	global_load_dwordx4 v[128:131], v95, s[86:87] offset:224
	v_pk_mul_f32 v[96:97], v[32:33], v[32:33]
	v_pk_fma_f32 v[96:97], v[34:35], v[34:35], v[96:97]
	v_pk_fma_f32 v[96:97], v[36:37], v[36:37], v[96:97]
	v_pk_fma_f32 v[96:97], v[38:39], v[38:39], v[96:97]
	v_pk_fma_f32 v[96:97], v[40:41], v[40:41], v[96:97]
	v_pk_fma_f32 v[96:97], v[42:43], v[42:43], v[96:97]
	v_pk_fma_f32 v[96:97], v[44:45], v[44:45], v[96:97]
	v_pk_fma_f32 v[96:97], v[46:47], v[46:47], v[96:97]
	v_pk_fma_f32 v[96:97], v[16:17], v[16:17], v[96:97]
	v_pk_fma_f32 v[96:97], v[18:19], v[18:19], v[96:97]
	v_pk_fma_f32 v[96:97], v[20:21], v[20:21], v[96:97]
	v_pk_fma_f32 v[96:97], v[22:23], v[22:23], v[96:97]
	v_pk_fma_f32 v[96:97], v[24:25], v[24:25], v[96:97]
	v_pk_fma_f32 v[96:97], v[26:27], v[26:27], v[96:97]
	v_pk_fma_f32 v[96:97], v[28:29], v[28:29], v[96:97]
	v_pk_fma_f32 v[96:97], v[30:31], v[30:31], v[96:97]
	v_add_f32_e32 v96, v96, v97
	v_mul_f32_e32 v97, v0, v0
	v_mul_f32_e32 v96, v96, v97
	ds_bpermute_b32 v97, v14, v96
	s_waitcnt vmcnt(0)
	v_pk_mul_f32 v[32:33], v[32:33], v[100:101]
	v_pk_mul_f32 v[34:35], v[34:35], v[102:103]
	v_pk_mul_f32 v[36:37], v[36:37], v[104:105]
	v_pk_mul_f32 v[38:39], v[38:39], v[106:107]
	v_pk_mul_f32 v[40:41], v[40:41], v[108:109]
	v_pk_mul_f32 v[42:43], v[42:43], v[110:111]
	v_pk_mul_f32 v[44:45], v[44:45], v[112:113]
	v_pk_mul_f32 v[46:47], v[46:47], v[114:115]
	v_pk_mul_f32 v[16:17], v[16:17], v[116:117]
	v_pk_mul_f32 v[18:19], v[18:19], v[118:119]
	v_pk_mul_f32 v[20:21], v[20:21], v[120:121]
	v_pk_mul_f32 v[22:23], v[22:23], v[122:123]
	v_pk_mul_f32 v[24:25], v[24:25], v[124:125]
	v_pk_mul_f32 v[26:27], v[26:27], v[126:127]
	v_pk_mul_f32 v[28:29], v[28:29], v[128:129]
	v_pk_mul_f32 v[30:31], v[30:31], v[130:131]
	s_waitcnt lgkmcnt(0)
	v_add_f32_e32 v96, v96, v97
	v_lshlrev_b32_e32 v94, 5, v188
	s_lshr_b32 s98, s12, 5
	v_add_u32_e32 v94, s98, v94
	s_add_u32 s98, s64, 0x13bec000
	s_addc_u32 s99, s65, 0
	s_mov_b64 s[100:101], exec
	s_mov_b32 exec_lo, -1
	s_mov_b32 exec_hi, 0
	global_store_dword v94, v96, s[98:99]
	s_mov_b64 exec, s[100:101]
	v_pk_mul_f32 v[4:5], v[38:39], v[0:1] op_sel_hi:[1,0]
	v_pk_mul_f32 v[6:7], v[36:37], v[0:1] op_sel_hi:[1,0]
	v_pk_mul_f32 v[8:9], v[34:35], v[0:1] op_sel_hi:[1,0]
	v_pk_mul_f32 v[10:11], v[32:33], v[0:1] op_sel_hi:[1,0]
	v_cvt_pk_bf16_f32 v12, v4, v5
	v_cvt_pk_bf16_f32 v13, v6, v7
	v_cvt_pk_bf16_f32 v15, v8, v9
	v_cvt_pk_bf16_f32 v32, v10, v11
	v_cndmask_b32_e64 v4, v32, v13, s[2:3]
	v_cndmask_b32_e64 v5, v15, v12, s[2:3]
	ds_bpermute_b32 v33, v14, v5
	ds_bpermute_b32 v34, v14, v4
	v_lshlrev_b64 v[4:5], 11, v[188:189]
	v_lshl_add_u64 v[6:7], v[2:3], 0, v[4:5]
	v_pk_mul_f32 v[8:9], v[44:45], v[0:1] op_sel_hi:[1,0]
	s_waitcnt lgkmcnt(1)
	v_cndmask_b32_e64 v5, v12, v33, s[2:3]
	s_waitcnt lgkmcnt(0)
	v_cndmask_b32_e64 v4, v13, v34, s[2:3]
	v_pk_mul_f32 v[12:13], v[40:41], v[0:1] op_sel_hi:[1,0]
	v_pk_mul_f32 v[2:3], v[46:47], v[0:1] op_sel_hi:[1,0]
	v_cvt_pk_bf16_f32 v8, v8, v9
	v_cvt_pk_bf16_f32 v37, v12, v13
	v_cvt_pk_bf16_f32 v35, v2, v3
	v_cndmask_b32_e64 v2, v37, v8, s[2:3]
	ds_bpermute_b32 v39, v14, v2
	v_pk_mul_f32 v[10:11], v[42:43], v[0:1] op_sel_hi:[1,0]
	v_cndmask_b32_e64 v2, v34, v32, s[2:3]
	v_cvt_pk_bf16_f32 v36, v10, v11
	v_cndmask_b32_e64 v3, v36, v35, s[2:3]
	ds_bpermute_b32 v38, v14, v3
	v_cndmask_b32_e64 v3, v33, v15, s[2:3]
	global_store_dwordx4 v[6:7], v[2:5], off
	v_pk_mul_f32 v[12:13], v[16:17], v[0:1] op_sel_hi:[1,0]
	v_pk_mul_f32 v[10:11], v[18:19], v[0:1] op_sel_hi:[1,0]
	s_waitcnt lgkmcnt(1)
	v_cndmask_b32_e64 v4, v8, v39, s[2:3]
	v_pk_mul_f32 v[8:9], v[20:21], v[0:1] op_sel_hi:[1,0]
	v_pk_mul_f32 v[2:3], v[22:23], v[0:1] op_sel_hi:[1,0]
	v_cvt_pk_bf16_f32 v8, v8, v9
	v_cvt_pk_bf16_f32 v17, v12, v13
	v_cvt_pk_bf16_f32 v15, v2, v3
	v_cndmask_b32_e64 v2, v17, v8, s[2:3]
	ds_bpermute_b32 v19, v14, v2
	v_cvt_pk_bf16_f32 v16, v10, v11
	v_cndmask_b32_e64 v3, v16, v15, s[2:3]
	s_waitcnt lgkmcnt(1)
	v_cndmask_b32_e64 v5, v35, v38, s[2:3]
	ds_bpermute_b32 v18, v14, v3
	v_cndmask_b32_e64 v3, v38, v36, s[2:3]
	v_cndmask_b32_e64 v2, v39, v37, s[2:3]
	global_store_dwordx4 v[6:7], v[2:5], off offset:32
	v_pk_mul_f32 v[10:11], v[26:27], v[0:1] op_sel_hi:[1,0]
	v_pk_mul_f32 v[12:13], v[24:25], v[0:1] op_sel_hi:[1,0]
	s_waitcnt lgkmcnt(1)
	v_cndmask_b32_e64 v4, v8, v19, s[2:3]
	v_pk_mul_f32 v[2:3], v[30:31], v[0:1] op_sel_hi:[1,0]
	v_pk_mul_f32 v[8:9], v[28:29], v[0:1] op_sel_hi:[1,0]
	v_cvt_pk_bf16_f32 v0, v2, v3
	v_cvt_pk_bf16_f32 v8, v8, v9
	v_cvt_pk_bf16_f32 v9, v10, v11
	v_cvt_pk_bf16_f32 v10, v12, v13
	v_cndmask_b32_e64 v2, v10, v8, s[2:3]
	v_cndmask_b32_e64 v3, v9, v0, s[2:3]
	ds_bpermute_b32 v11, v14, v3
	ds_bpermute_b32 v12, v14, v2
	s_waitcnt lgkmcnt(2)
	v_cndmask_b32_e64 v5, v15, v18, s[2:3]
	v_cndmask_b32_e64 v3, v18, v16, s[2:3]
	v_cndmask_b32_e64 v2, v19, v17, s[2:3]
	global_store_dwordx4 v[6:7], v[2:5], off offset:64
	s_waitcnt lgkmcnt(1)
	s_nop 0
	v_cndmask_b32_e64 v5, v0, v11, s[2:3]
	s_waitcnt lgkmcnt(0)
	v_cndmask_b32_e64 v4, v8, v12, s[2:3]
	v_cndmask_b32_e64 v3, v11, v9, s[2:3]
	v_cndmask_b32_e64 v2, v12, v10, s[2:3]
	global_store_dwordx4 v[6:7], v[2:5], off offset:96
	s_and_saveexec_b64 s[18:19], s[0:1]
	s_cbranch_execz .LBB0_840
	v_mov_b32_e32 v0, s24
	ds_write_b32 v0, v200
	s_branch .LBB0_840

; #define SEAM(k) do { if (IN(k) && IN((k) + 1)) xcd_barrier(xbar); } while (0)
; #define PH(k) if (IN(k)) for (int rep_ = 0; rep_ < (((PHREP >> (k)) & 1) ? 2 : 1); ++rep_)
; __global__ void __launch_bounds__(512, 2) mk_fwd(Args a) {
;     ...
;     PH(8) {
;         for (int m = gw; m < M; m += 4 * NGW) mla_norm_rows<4>(P, (const float*)a.in[13], m, NGW, lane);
;     }
;     SEAM(8);
.LBB0_921:
	s_cmp_lt_i32 s66, 9
	s_cselect_b64 s[2:3], -1, 0
	s_and_b64 s[2:3], s[2:3], s[0:1]
	s_andn2_b64 vcc, exec, s[2:3]
	s_branch .LBB0_925
.LBB0_925:
	s_cmp_gt_i32 s67, 9
	s_cselect_b64 s[0:1], -1, 0
	s_and_b64 s[2:3], s[2:3], s[0:1]
	v_readlane_b32 s56, v253, 43
	v_readlane_b32 s78, v253, 49
	v_readlane_b32 s52, v253, 41
	s_andn2_b64 vcc, exec, s[2:3]
	v_readlane_b32 s57, v253, 44
	v_readlane_b32 s79, v253, 50
	v_readlane_b32 s53, v253, 42
	s_branch .LBB0_975

; #define PH(k) if (IN(k)) for (int rep_ = 0; rep_ < (((PHREP >> (k)) & 1) ? 2 : 1); ++rep_)
; template <int NR> DI void mla_norm_rows(bf16* A, const float* g_mla, int m0, int mstride, int lane) {
;     ...
;         float s2 = 0.f;
; #pragma unroll
;         for (int i = 0; i < 8; ++i) s2 += v[i] * v[i];
;         const float rr = rsqrtf(wave_sum(s2) * (1.f / 512.f) + EPS);
; __global__ void __launch_bounds__(512, 2) mk_fwd(Args a) {
;     ...
;     PH(9) {
;         pg8::Gemm g{P, WOUT, M, 1024, 1024}; pg8::StaticOrder S; S.init(M, 1024, G, bid);
;         pg8::EpiBf16Sq E{Q, ROWSQ};
;         pg8::gemm_phase<pg8::EpiBf16Sq, pg8::StaticOrder, true, true>(lds, g, S, E);
;     }
.LBB0_991:
	s_cmp_eq_u32 s48, -2
	s_cbranch_scc0 .Lp9h_a
	v_lshl_add_u32 v144, s22, 8, v148
	v_lshlrev_b32_e32 v144, 5, v144
	v_lshrrev_b32_e32 v145, 4, v154
	v_lshl_add_u32 v144, v145, 3, v144
	s_add_u32 s98, s64, 0x13bec000
	s_addc_u32 s99, s65, 0
	s_add_u32 s100, s98, 0x1000
	s_addc_u32 s101, s99, 0
	global_load_dwordx2 v[230:231], v144, s[98:99]
	global_load_dwordx2 v[232:233], v144, s[98:99] offset:512
	global_load_dwordx2 v[234:235], v144, s[98:99] offset:1024
	global_load_dwordx2 v[236:237], v144, s[98:99] offset:1536
	global_load_dwordx2 v[238:239], v144, s[100:101]
	global_load_dwordx2 v[240:241], v144, s[100:101] offset:512
	global_load_dwordx2 v[242:243], v144, s[100:101] offset:1024
	global_load_dwordx2 v[244:245], v144, s[100:101] offset:1536
.Lp9h_a:
	s_cmp_eq_u32 s48, 6
	s_cbranch_scc0 .Lp9h_b
	s_waitcnt vmcnt(8)
	v_add_f32_e32 v230, v230, v231
	v_add_f32_e32 v232, v232, v233
	v_add_f32_e32 v234, v234, v235
	v_add_f32_e32 v236, v236, v237
	v_add_f32_e32 v238, v238, v239
	v_add_f32_e32 v240, v240, v241
	v_add_f32_e32 v242, v242, v243
	v_add_f32_e32 v244, v244, v245
	v_xor_b32_e32 v144, 16, v154
	v_lshlrev_b32_e32 v144, 2, v144
	v_xor_b32_e32 v145, 32, v154
	v_lshlrev_b32_e32 v145, 2, v145
	ds_bpermute_b32 v156, v144, v230
	ds_bpermute_b32 v157, v144, v232
	ds_bpermute_b32 v158, v144, v234
	ds_bpermute_b32 v159, v144, v236
	ds_bpermute_b32 v160, v144, v238
	ds_bpermute_b32 v161, v144, v240
	ds_bpermute_b32 v162, v144, v242
	ds_bpermute_b32 v163, v144, v244
	s_waitcnt lgkmcnt(0)
	v_add_f32_e32 v230, v230, v156
	v_add_f32_e32 v232, v232, v157
	v_add_f32_e32 v234, v234, v158
	v_add_f32_e32 v236, v236, v159
	v_add_f32_e32 v238, v238, v160
	v_add_f32_e32 v240, v240, v161
	v_add_f32_e32 v242, v242, v162
	v_add_f32_e32 v244, v244, v163
	ds_bpermute_b32 v156, v145, v230
	ds_bpermute_b32 v157, v145, v232
	ds_bpermute_b32 v158, v145, v234
	ds_bpermute_b32 v159, v145, v236
	ds_bpermute_b32 v160, v145, v238
	ds_bpermute_b32 v161, v145, v240
	ds_bpermute_b32 v162, v145, v242
	ds_bpermute_b32 v163, v145, v244
	s_waitcnt lgkmcnt(0)
	v_add_f32_e32 v230, v230, v156
	v_add_f32_e32 v232, v232, v157
	v_add_f32_e32 v234, v234, v158
	v_add_f32_e32 v236, v236, v159
	v_add_f32_e32 v238, v238, v160
	v_add_f32_e32 v240, v240, v161
	v_add_f32_e32 v242, v242, v162
	v_add_f32_e32 v244, v244, v163
	v_mov_b32_e32 v146, 0x3b000000
	v_mov_b32_e32 v147, 0x358637bd
	v_fma_f32 v230, v230, v146, v147
	v_fma_f32 v232, v232, v146, v147
	v_fma_f32 v234, v234, v146, v147
	v_fma_f32 v236, v236, v146, v147
	v_fma_f32 v238, v238, v146, v147
	v_fma_f32 v240, v240, v146, v147
	v_fma_f32 v242, v242, v146, v147
	v_fma_f32 v244, v244, v146, v147
	v_rsq_f32_e32 v230, v230
	v_rsq_f32_e32 v232, v232
	v_rsq_f32_e32 v234, v234
	v_rsq_f32_e32 v236, v236
	v_rsq_f32_e32 v238, v238
	v_rsq_f32_e32 v240, v240
	v_rsq_f32_e32 v242, v242
	v_rsq_f32_e32 v244, v244
	s_nop 1
	v_pk_mul_f32 v[112:113], v[112:113], v[230:231] op_sel_hi:[1,0]
	v_pk_mul_f32 v[114:115], v[114:115], v[230:231] op_sel_hi:[1,0]
	v_pk_mul_f32 v[116:117], v[116:117], v[230:231] op_sel_hi:[1,0]
	v_pk_mul_f32 v[118:119], v[118:119], v[230:231] op_sel_hi:[1,0]
	v_pk_mul_f32 v[120:121], v[120:121], v[230:231] op_sel_hi:[1,0]
	v_pk_mul_f32 v[122:123], v[122:123], v[230:231] op_sel_hi:[1,0]
	v_pk_mul_f32 v[124:125], v[124:125], v[230:231] op_sel_hi:[1,0]
	v_pk_mul_f32 v[126:127], v[126:127], v[230:231] op_sel_hi:[1,0]
	v_pk_mul_f32 v[96:97], v[96:97], v[232:233] op_sel_hi:[1,0]
	v_pk_mul_f32 v[98:99], v[98:99], v[232:233] op_sel_hi:[1,0]
	v_pk_mul_f32 v[100:101], v[100:101], v[232:233] op_sel_hi:[1,0]
	v_pk_mul_f32 v[102:103], v[102:103], v[232:233] op_sel_hi:[1,0]
	v_pk_mul_f32 v[104:105], v[104:105], v[232:233] op_sel_hi:[1,0]
	v_pk_mul_f32 v[106:107], v[106:107], v[232:233] op_sel_hi:[1,0]
	v_pk_mul_f32 v[108:109], v[108:109], v[232:233] op_sel_hi:[1,0]
	v_pk_mul_f32 v[110:111], v[110:111], v[232:233] op_sel_hi:[1,0]
	v_pk_mul_f32 v[80:81], v[80:81], v[234:235] op_sel_hi:[1,0]
	v_pk_mul_f32 v[82:83], v[82:83], v[234:235] op_sel_hi:[1,0]
	v_pk_mul_f32 v[84:85], v[84:85], v[234:235] op_sel_hi:[1,0]
	v_pk_mul_f32 v[86:87], v[86:87], v[234:235] op_sel_hi:[1,0]
	v_pk_mul_f32 v[88:89], v[88:89], v[234:235] op_sel_hi:[1,0]
	v_pk_mul_f32 v[90:91], v[90:91], v[234:235] op_sel_hi:[1,0]
	v_pk_mul_f32 v[92:93], v[92:93], v[234:235] op_sel_hi:[1,0]
	v_pk_mul_f32 v[94:95], v[94:95], v[234:235] op_sel_hi:[1,0]
	v_pk_mul_f32 v[64:65], v[64:65], v[236:237] op_sel_hi:[1,0]
	v_pk_mul_f32 v[66:67], v[66:67], v[236:237] op_sel_hi:[1,0]
	v_pk_mul_f32 v[68:69], v[68:69], v[236:237] op_sel_hi:[1,0]
	v_pk_mul_f32 v[70:71], v[70:71], v[236:237] op_sel_hi:[1,0]
	v_pk_mul_f32 v[72:73], v[72:73], v[236:237] op_sel_hi:[1,0]
	v_pk_mul_f32 v[74:75], v[74:75], v[236:237] op_sel_hi:[1,0]
	v_pk_mul_f32 v[76:77], v[76:77], v[236:237] op_sel_hi:[1,0]
	v_pk_mul_f32 v[78:79], v[78:79], v[236:237] op_sel_hi:[1,0]
	v_pk_mul_f32 v[48:49], v[48:49], v[238:239] op_sel_hi:[1,0]
	v_pk_mul_f32 v[50:51], v[50:51], v[238:239] op_sel_hi:[1,0]
	v_pk_mul_f32 v[52:53], v[52:53], v[238:239] op_sel_hi:[1,0]
	v_pk_mul_f32 v[54:55], v[54:55], v[238:239] op_sel_hi:[1,0]
	v_pk_mul_f32 v[56:57], v[56:57], v[238:239] op_sel_hi:[1,0]
	v_pk_mul_f32 v[58:59], v[58:59], v[238:239] op_sel_hi:[1,0]
	v_pk_mul_f32 v[60:61], v[60:61], v[238:239] op_sel_hi:[1,0]
	v_pk_mul_f32 v[62:63], v[62:63], v[238:239] op_sel_hi:[1,0]
	v_pk_mul_f32 v[32:33], v[32:33], v[240:241] op_sel_hi:[1,0]
	v_pk_mul_f32 v[34:35], v[34:35], v[240:241] op_sel_hi:[1,0]
	v_pk_mul_f32 v[36:37], v[36:37], v[240:241] op_sel_hi:[1,0]
	v_pk_mul_f32 v[38:39], v[38:39], v[240:241] op_sel_hi:[1,0]
	v_pk_mul_f32 v[40:41], v[40:41], v[240:241] op_sel_hi:[1,0]
	v_pk_mul_f32 v[42:43], v[42:43], v[240:241] op_sel_hi:[1,0]
	v_pk_mul_f32 v[44:45], v[44:45], v[240:241] op_sel_hi:[1,0]
	v_pk_mul_f32 v[46:47], v[46:47], v[240:241] op_sel_hi:[1,0]
	v_pk_mul_f32 v[16:17], v[16:17], v[242:243] op_sel_hi:[1,0]
	v_pk_mul_f32 v[18:19], v[18:19], v[242:243] op_sel_hi:[1,0]
	v_pk_mul_f32 v[20:21], v[20:21], v[242:243] op_sel_hi:[1,0]
	v_pk_mul_f32 v[22:23], v[22:23], v[242:243] op_sel_hi:[1,0]
	v_pk_mul_f32 v[24:25], v[24:25], v[242:243] op_sel_hi:[1,0]
	v_pk_mul_f32 v[26:27], v[26:27], v[242:243] op_sel_hi:[1,0]
	v_pk_mul_f32 v[28:29], v[28:29], v[242:243] op_sel_hi:[1,0]
	v_pk_mul_f32 v[30:31], v[30:31], v[242:243] op_sel_hi:[1,0]
	v_pk_mul_f32 v[0:1], v[0:1], v[244:245] op_sel_hi:[1,0]
	v_pk_mul_f32 v[2:3], v[2:3], v[244:245] op_sel_hi:[1,0]
	v_pk_mul_f32 v[4:5], v[4:5], v[244:245] op_sel_hi:[1,0]
	v_pk_mul_f32 v[6:7], v[6:7], v[244:245] op_sel_hi:[1,0]
	v_pk_mul_f32 v[8:9], v[8:9], v[244:245] op_sel_hi:[1,0]
	v_pk_mul_f32 v[10:11], v[10:11], v[244:245] op_sel_hi:[1,0]
	v_pk_mul_f32 v[12:13], v[12:13], v[244:245] op_sel_hi:[1,0]
	v_pk_mul_f32 v[14:15], v[14:15], v[244:245] op_sel_hi:[1,0]
	s_nop 1
